# FFN-in sample-path sgemm unit K-split 5+3 across a workgroup pair (tagged granules)
# baseline (speedup 1.0000x reference)
.LBB0_2429:
	s_or_b64 exec, exec, s[2:3]
	s_lshr_b32 s2, s20, 25
	s_mul_i32 s2, s2, s19
	s_sub_i32 s2, 0x80, s2
	s_sub_i32 s3, s2, s19
	s_cmp_ge_u32 s2, s19
	s_cselect_b32 s2, s3, s2
	s_sub_i32 s3, s2, s19
	s_cmp_ge_u32 s2, s19
	s_cselect_b32 s8, s3, s2
	s_sub_i32 s2, s46, s8
	s_ashr_i32 s3, s2, 31
	s_abs_i32 s2, s2
	s_mul_hi_u32 s28, s2, s20
	s_mul_i32 s28, s28, s19
	s_sub_i32 s2, s2, s28
	s_sub_i32 s28, s2, s19
	s_cmp_ge_u32 s2, s19
	s_cselect_b32 s2, s28, s2
	s_sub_i32 s28, s2, s19
	s_cmp_ge_u32 s2, s19
	s_cselect_b32 s2, s28, s2
	s_xor_b32 s2, s2, s3
	s_sub_i32 s28, s2, s3
	s_mov_b32 s100, 0
	s_mov_b32 s101, 0
	s_cmpk_gt_i32 s28, 0x57
	s_cbranch_scc0 .LBB0_2437
	s_cmpk_gt_i32 s28, 0xaf
	s_cbranch_scc1 .LBB0_2430
	s_sub_i32 s28, s28, 0x58
	s_movk_i32 s100, 0xa0
	s_branch .LBB0_2437

.Lfi_hi:
	ds_read_b32 v238, v100
	ds_read_b32 v240, v100 offset:4224
	ds_read_b32 v242, v102
	ds_read_b32 v244, v102 offset:4224
	v_mov_b32_e32 v239, s60
	v_mov_b32_e32 v241, s60
	v_mov_b32_e32 v243, s60
	v_mov_b32_e32 v245, s60
	s_waitcnt lgkmcnt(0)
	global_store_dwordx2 v[236:237], v[238:239], off sc1
	global_store_dwordx2 v[236:237], v[240:241], off offset:8 sc1
	global_store_dwordx2 v[236:237], v[242:243], off offset:16 sc1
	global_store_dwordx2 v[236:237], v[244:245], off offset:24 sc1
	s_add_i32 s28, s28, s45
	s_cmpk_lt_i32 s28, 0x58
	s_branch .Lfi_end
.LBB0_2436:
	s_or_b64 exec, exec, s[60:61]
	v_ffbh_u32_e32 v0, v37
	v_min_u32_e32 v3, 32, v0
	v_lshlrev_b64 v[0:1], v3, v[36:37]
	v_min_u32_e32 v0, 1, v0
	v_or_b32_e32 v0, v1, v0
	v_cvt_f32_u32_e32 v0, v0
	v_sub_u32_e32 v1, 32, v3
	s_waitcnt lgkmcnt(0)
	s_barrier
	s_sub_u32 s60, s86, 0x24b80000
	s_subb_u32 s61, s87, 0
	s_lshl_b32 s2, s28, 14
	s_add_u32 s2, s2, 0x10000
	s_cmp_lt_u32 s28, 60
	s_cbranch_scc1 .Lfi_r1
	v_readlane_b32 s3, v254, 49
	s_nop 3
	s_cmp_eq_u32 s3, 1
	s_cselect_b32 s3, 0x80000, 0
	s_sub_i32 s2, s28, 60
	s_lshl_b32 s2, s2, 14
	s_add_u32 s2, s2, 0x300000
	s_add_u32 s2, s2, s3
.Lfi_r1:
	s_add_u32 s60, s60, s2
	s_addc_u32 s61, s61, 0
	v_lshlrev_b32_e32 v236, 5, v79
	v_mov_b32_e32 v237, 0
	v_lshl_add_u64 v[236:237], v[236:237], 0, s[60:61]
	v_readlane_b32 s60, v254, 49
	s_nop 3
	s_addk_i32 s60, 0x101
	s_cmp_lg_u32 s100, 0
	s_cbranch_scc1 .Lfi_hi
	s_mov_b32 s61, 0
.Lfi_poll:
	global_load_dwordx2 v[238:239], v[236:237], off sc1
	global_load_dwordx2 v[240:241], v[236:237], off offset:8 sc1
	global_load_dwordx2 v[242:243], v[236:237], off offset:16 sc1
	global_load_dwordx2 v[244:245], v[236:237], off offset:24 sc1
	s_waitcnt vmcnt(0)
	v_cmp_ne_u32_e32 vcc, s60, v239
	v_cmp_ne_u32_e64 s[2:3], s60, v241
	s_or_b64 vcc, vcc, s[2:3]
	v_cmp_ne_u32_e64 s[2:3], s60, v243
	s_or_b64 vcc, vcc, s[2:3]
	v_cmp_ne_u32_e64 s[2:3], s60, v245
	s_or_b64 vcc, vcc, s[2:3]
	s_cbranch_vccz .Lfi_got
	s_add_i32 s61, s61, 1
	s_cmp_lt_u32 s61, 0x4000
	s_cbranch_scc0 .Lfi_got
	s_sleep 2
	s_branch .Lfi_poll
.Lfi_got:
	v_ldexp_f32 v0, v0, v1
	ds_read_b32 v2, v100
	v_fmamk_f32 v0, v0, 0x2e800000, v214
	v_rsq_f32_e32 v0, v0
	s_add_i32 s28, s28, s45
	s_cmpk_lt_i32 s28, 0x58
	s_waitcnt lgkmcnt(0)
	v_add_f32_e32 v2, v2, v238
	v_mul_f32_e32 v1, v0, v2
	ds_read_b32 v2, v100 offset:4224
	s_waitcnt lgkmcnt(0)
	v_add_f32_e32 v2, v2, v240
	v_mul_f32_e32 v0, v0, v2
	v_mul_f32_e32 v2, 0xbfb8aa3b, v1
	v_exp_f32_e32 v2, v2
	s_nop 0
	v_add_f32_e32 v2, 1.0, v2
	v_rcp_f32_e32 v2, v2
	s_nop 0
	v_mul_f32_e32 v1, v1, v2
	v_mul_f32_e32 v0, v0, v1
	v_cvt_pk_bf16_f32 v2, v0, v33
	v_add_u32_e32 v0, s29, v101
	v_ashrrev_i32_e32 v1, 31, v0
	v_lshl_add_u64 v[0:1], v[0:1], 1, s[86:87]
	global_store_short v[0:1], v2, off
	v_ffbh_u32_e32 v0, v35
	v_min_u32_e32 v3, 32, v0
	v_lshlrev_b64 v[0:1], v3, v[34:35]
	v_min_u32_e32 v0, 1, v0
	v_or_b32_e32 v0, v1, v0
	v_cvt_f32_u32_e32 v0, v0
	v_sub_u32_e32 v1, 32, v3
	ds_read_b32 v2, v102
	v_ldexp_f32 v0, v0, v1
	v_fmamk_f32 v0, v0, 0x2e800000, v214
	v_rsq_f32_e32 v0, v0
	s_waitcnt lgkmcnt(0)
	v_add_f32_e32 v2, v2, v242
	v_mul_f32_e32 v1, v0, v2
	ds_read_b32 v2, v102 offset:4224
	s_waitcnt lgkmcnt(0)
	v_add_f32_e32 v2, v2, v244
	v_mul_f32_e32 v0, v0, v2
	v_mul_f32_e32 v2, 0xbfb8aa3b, v1
	v_exp_f32_e32 v2, v2
	s_nop 0
	v_add_f32_e32 v2, 1.0, v2
	v_rcp_f32_e32 v2, v2
	s_nop 0
	v_mul_f32_e32 v1, v1, v2
	v_mul_f32_e32 v0, v0, v1
	v_cvt_pk_bf16_f32 v2, v0, v33
	v_add_u32_e32 v0, s29, v103
	v_ashrrev_i32_e32 v1, 31, v0
	v_lshl_add_u64 v[0:1], v[0:1], 1, s[86:87]
	global_store_short v[0:1], v2, off
.Lfi_end:
	s_barrier
	s_cbranch_scc0 .LBB0_2430
.LBB0_2437:
	s_lshl_b32 s2, s28, 6
	s_lshl_b32 s29, s28, 5
	s_and_b32 s2, s2, 0xffffff00
	s_and_b32 s3, s29, 0x60
	s_or_b32 s2, s3, s2
	v_or_b32_e32 v4, s2, v80
	v_lshl_add_u64 v[248:249], v[42:43], 0, s[100:101]
	v_ashrrev_i32_e32 v5, 31, v4
	v_lshlrev_b64 v[0:1], 11, v[4:5]
	v_lshl_add_u64 v[54:55], v[44:45], 0, v[0:1]
	v_lshl_add_u64 v[54:55], v[54:55], 0, s[100:101]
	v_or_b32_e32 v4, 0x80, v4
	v_ashrrev_i32_e32 v5, 31, v4
	v_lshlrev_b64 v[4:5], 11, v[4:5]
	v_lshl_add_u64 v[108:109], v[44:45], 0, v[4:5]
	v_lshl_add_u64 v[108:109], v[108:109], 0, s[100:101]
	v_add_u32_e32 v32, 0x8000, v82
	global_load_dwordx4 v[112:115], v[248:249], off
	global_load_dwordx4 v[116:119], v[54:55], off
	global_load_dwordx4 v[120:123], v[108:109], off
	global_load_dwordx4 v[124:127], v[248:249], off offset:32
	global_load_dwordx4 v[140:143], v[54:55], off offset:32
	global_load_dwordx4 v[144:147], v[108:109], off offset:32
	global_load_dwordx4 v[148:151], v[248:249], off offset:64
	global_load_dwordx4 v[160:163], v[54:55], off offset:64
	global_load_dwordx4 v[164:167], v[108:109], off offset:64
	global_load_dwordx4 v[168:171], v[248:249], off offset:96
	global_load_dwordx4 v[172:175], v[54:55], off offset:96
	global_load_dwordx4 v[176:179], v[108:109], off offset:96
	global_load_dwordx4 v[180:183], v[248:249], off offset:128
	global_load_dwordx4 v[184:187], v[54:55], off offset:128
	global_load_dwordx4 v[188:191], v[108:109], off offset:128
	global_load_dwordx2 v[36:37], v[38:39], off
	global_load_dwordx2 v[34:35], v[40:41], off
	s_waitcnt vmcnt(14)
	v_mfma_f32_32x32x16_bf16 v[0:15], v[112:115], v[116:119], 0
	v_mfma_f32_32x32x16_bf16 v[16:31], v[112:115], v[120:123], 0
	s_waitcnt vmcnt(11)
	v_mfma_f32_32x32x16_bf16 v[0:15], v[124:127], v[140:143], v[0:15]
	v_mfma_f32_32x32x16_bf16 v[16:31], v[124:127], v[144:147], v[16:31]
	s_waitcnt vmcnt(8)
	v_mfma_f32_32x32x16_bf16 v[0:15], v[148:151], v[160:163], v[0:15]
	v_mfma_f32_32x32x16_bf16 v[16:31], v[148:151], v[164:167], v[16:31]
	s_cmp_lg_u32 s100, 0
	s_cbranch_scc1 .Lfi_s
	s_waitcnt vmcnt(5)
	v_mfma_f32_32x32x16_bf16 v[0:15], v[168:171], v[172:175], v[0:15]
	v_mfma_f32_32x32x16_bf16 v[16:31], v[168:171], v[176:179], v[16:31]
	s_waitcnt vmcnt(2)
	v_mfma_f32_32x32x16_bf16 v[0:15], v[180:183], v[184:187], v[0:15]
	v_mfma_f32_32x32x16_bf16 v[16:31], v[180:183], v[188:191], v[16:31]
.Lfi_s:
	s_waitcnt vmcnt(0)
	v_add_u32_e32 v46, 0x8400, v82
	v_add_u32_e32 v47, 0x8800, v82
	v_add_u32_e32 v48, 0x8c00, v82
	s_nop 8
	ds_write2_b32 v32, v0, v1 offset1:32
	ds_write2_b32 v32, v2, v3 offset0:64 offset1:96
	ds_write2_b32 v46, v4, v5 offset1:32
	ds_write2_b32 v46, v6, v7 offset0:64 offset1:96
	ds_write2_b32 v47, v8, v9 offset1:32
	ds_write2_b32 v47, v10, v11 offset0:64 offset1:96
	ds_write2_b32 v48, v12, v13 offset1:32
	ds_write2_b32 v48, v14, v15 offset0:64 offset1:96
	ds_write_b32 v83, v16
	ds_write_b32 v84, v17
	ds_write_b32 v85, v18
	ds_write_b32 v86, v19
	ds_write_b32 v87, v20
	ds_write_b32 v88, v21
	ds_write_b32 v89, v22
	ds_write_b32 v90, v23
	ds_write_b32 v91, v24
	ds_write_b32 v92, v25
	ds_write_b32 v93, v26
	ds_write_b32 v95, v27
	ds_write_b32 v96, v28
	ds_write_b32 v97, v29
	ds_write_b32 v98, v30
	ds_write_b32 v99, v31
	s_waitcnt lgkmcnt(0)
	s_barrier
	s_and_saveexec_b64 s[60:61], s[38:39]
	s_movk_i32 s31, 0x1080
	s_cbranch_execz .LBB0_2436
	s_mov_b64 s[2:3], 0
	v_mov_b32_e32 v0, v79
